# v43: v42 + int8 GEMM1: leading half's end-of-unit alignment barrier moved after the epilogue's common prefix (address math and scale copies run during its wait)
# speedup vs baseline: 1.0058x; 1.0058x over previous
.Lspf_j2:
	s_waitcnt lgkmcnt(0)
	s_barrier
	s_waitcnt lgkmcnt(0)
	v_mfma_i32_16x16x64_i8 v[142:145], v[34:37], v[174:177], v[142:145]
	v_mfma_i32_16x16x64_i8 v[142:145], v[38:41], v[178:181], v[142:145]
	v_mfma_i32_16x16x64_i8 v[134:137], v[34:37], v[182:185], v[134:137]
	v_mfma_i32_16x16x64_i8 v[134:137], v[38:41], v[186:189], v[134:137]
	v_mfma_i32_16x16x64_i8 v[122:125], v[34:37], v[190:193], v[122:125]
	v_mfma_i32_16x16x64_i8 v[122:125], v[38:41], v[200:203], v[122:125]
	v_mfma_i32_16x16x64_i8 v[106:109], v[34:37], v[204:207], v[106:109]
	v_mfma_i32_16x16x64_i8 v[106:109], v[38:41], v[208:211], v[106:109]
	v_mfma_i32_16x16x64_i8 v[138:141], v[58:61], v[174:177], v[138:141]
	v_mfma_i32_16x16x64_i8 v[138:141], v[62:65], v[178:181], v[138:141]
	v_mfma_i32_16x16x64_i8 v[130:133], v[58:61], v[182:185], v[130:133]
	v_mfma_i32_16x16x64_i8 v[130:133], v[62:65], v[186:189], v[130:133]
	v_mfma_i32_16x16x64_i8 v[114:117], v[58:61], v[190:193], v[114:117]
	v_mfma_i32_16x16x64_i8 v[114:117], v[62:65], v[200:203], v[114:117]
	v_mfma_i32_16x16x64_i8 v[98:101], v[58:61], v[204:207], v[98:101]
	v_mfma_i32_16x16x64_i8 v[98:101], v[62:65], v[208:211], v[98:101]
	v_mfma_i32_16x16x64_i8 v[126:129], v[146:149], v[174:177], v[126:129]
	v_mfma_i32_16x16x64_i8 v[126:129], v[150:153], v[178:181], v[126:129]
	v_mfma_i32_16x16x64_i8 v[110:113], v[146:149], v[182:185], v[110:113]
	v_mfma_i32_16x16x64_i8 v[110:113], v[150:153], v[186:189], v[110:113]
	v_mfma_i32_16x16x64_i8 v[94:97], v[146:149], v[190:193], v[94:97]
	v_mfma_i32_16x16x64_i8 v[94:97], v[150:153], v[200:203], v[94:97]
	v_mfma_i32_16x16x64_i8 v[86:89], v[146:149], v[204:207], v[86:89]
	v_mfma_i32_16x16x64_i8 v[86:89], v[150:153], v[208:211], v[86:89]
	v_mfma_i32_16x16x64_i8 v[118:121], v[154:157], v[174:177], v[118:121]
	v_mfma_i32_16x16x64_i8 v[118:121], v[158:161], v[178:181], v[118:121]
	v_mfma_i32_16x16x64_i8 v[102:105], v[154:157], v[182:185], v[102:105]
	v_mfma_i32_16x16x64_i8 v[102:105], v[158:161], v[186:189], v[102:105]
	v_mfma_i32_16x16x64_i8 v[90:93], v[154:157], v[190:193], v[90:93]
	v_mfma_i32_16x16x64_i8 v[90:93], v[158:161], v[200:203], v[90:93]
	v_mfma_i32_16x16x64_i8 v[82:85], v[154:157], v[204:207], v[82:85]
	v_mfma_i32_16x16x64_i8 v[82:85], v[158:161], v[208:211], v[82:85]
	s_barrier
	s_add_i32 s30, s42, s81
	s_add_u32 s98, s28, 0x80
	s_addc_u32 s99, s29, 0
	s_mov_b32 m0, s30
	ds_read_b128 v[174:177], v250 offset:49152
	ds_read_b128 v[178:181], v250 offset:50176
	ds_read_b128 v[182:185], v250 offset:51200
	ds_read_b128 v[186:189], v250 offset:52224
	ds_read_b128 v[190:193], v250 offset:53248
	ds_read_b128 v[200:203], v250 offset:54272
	ds_read_b128 v[204:207], v250 offset:55296
	ds_read_b128 v[208:211], v250 offset:56320
	global_load_lds_dwordx4 v164, s[98:99]
	s_add_i32 m0, s30, 0x2000
	s_add_u32 s28, s28, 0x80080
	s_addc_u32 s29, s29, 0
	s_add_i32 s30, s43, s81
	global_load_lds_dwordx4 v168, s[98:99]
	s_mov_b32 m0, s30
	s_nop 0
	global_load_lds_dwordx4 v164, s[28:29]
	s_add_i32 m0, s30, 0x2000
	s_nop 0
	global_load_lds_dwordx4 v168, s[28:29]
	s_waitcnt vmcnt(6)
	s_waitcnt lgkmcnt(0)
	s_barrier
	s_waitcnt lgkmcnt(0)
	v_mfma_i32_16x16x64_i8 v[78:81], v[34:37], v[174:177], v[78:81]
	v_mfma_i32_16x16x64_i8 v[78:81], v[38:41], v[178:181], v[78:81]
	v_mfma_i32_16x16x64_i8 v[70:73], v[34:37], v[182:185], v[70:73]
	v_mfma_i32_16x16x64_i8 v[70:73], v[38:41], v[186:189], v[70:73]
	v_mfma_i32_16x16x64_i8 v[54:57], v[34:37], v[190:193], v[54:57]
	v_mfma_i32_16x16x64_i8 v[54:57], v[38:41], v[200:203], v[54:57]
	v_mfma_i32_16x16x64_i8 v[2:5], v[34:37], v[204:207], v[2:5]
	v_mfma_i32_16x16x64_i8 v[38:41], v[38:41], v[208:211], v[2:5]
	v_mfma_i32_16x16x64_i8 v[74:77], v[58:61], v[174:177], v[74:77]
	v_mfma_i32_16x16x64_i8 v[74:77], v[62:65], v[178:181], v[74:77]
	v_mfma_i32_16x16x64_i8 v[66:69], v[58:61], v[182:185], v[66:69]
	v_mfma_i32_16x16x64_i8 v[66:69], v[62:65], v[186:189], v[66:69]
	v_mfma_i32_16x16x64_i8 v[50:53], v[58:61], v[190:193], v[50:53]
	v_mfma_i32_16x16x64_i8 v[50:53], v[62:65], v[200:203], v[50:53]
	v_mfma_i32_16x16x64_i8 v[2:5], v[58:61], v[204:207], v[6:9]
	v_mfma_i32_16x16x64_i8 v[34:37], v[62:65], v[208:211], v[2:5]
	v_mfma_i32_16x16x64_i8 v[2:5], v[146:149], v[174:177], v[10:13]
	v_mfma_i32_16x16x64_i8 v[62:65], v[150:153], v[178:181], v[2:5]
	v_mfma_i32_16x16x64_i8 v[2:5], v[154:157], v[174:177], v[14:17]
	v_mfma_i32_16x16x64_i8 v[58:61], v[158:161], v[178:181], v[2:5]
	v_mfma_i32_16x16x64_i8 v[2:5], v[146:149], v[182:185], v[46:49]
	v_mfma_i32_16x16x64_i8 v[46:49], v[150:153], v[186:189], v[2:5]
	v_mfma_i32_16x16x64_i8 v[2:5], v[154:157], v[182:185], v[42:45]
	v_mfma_i32_16x16x64_i8 v[42:45], v[158:161], v[186:189], v[2:5]
	v_mfma_i32_16x16x64_i8 v[2:5], v[146:149], v[190:193], v[30:33]
	v_mfma_i32_16x16x64_i8 v[30:33], v[150:153], v[200:203], v[2:5]
	v_mfma_i32_16x16x64_i8 v[2:5], v[154:157], v[190:193], v[26:29]
	v_mfma_i32_16x16x64_i8 v[26:29], v[158:161], v[200:203], v[2:5]
	v_mfma_i32_16x16x64_i8 v[2:5], v[146:149], v[204:207], v[22:25]
	v_mfma_i32_16x16x64_i8 v[22:25], v[150:153], v[208:211], v[2:5]
	v_mfma_i32_16x16x64_i8 v[2:5], v[154:157], v[204:207], v[18:21]
	v_mfma_i32_16x16x64_i8 v[18:21], v[158:161], v[208:211], v[2:5]
	s_barrier
	s_add_i32 s41, s41, 2
	s_add_u32 s0, s0, 0x100
	s_addc_u32 s1, s1, 0
	s_add_u32 s35, s35, 0x100
	s_addc_u32 s40, s40, 0
	s_cmp_gt_u32 s41, 29
	s_cbranch_scc0 .LBB0_300
.LBB0_303:
	v_readlane_b32 s18, v255, 8
	v_readlane_b32 s19, v255, 9
	s_mov_b64 s[0:1], -1
	s_andn2_b64 vcc, exec, s[18:19]
	v_cndmask_b32_e64 v0, 0, 1, s[18:19]
	v_cmp_ne_u32_e64 s[40:41], 1, v0
	v_mbcnt_lo_u32_b32 v2, -1, 0
	v_mbcnt_hi_u32_b32 v2, -1, v2
	s_cbranch_vccz .LBB0_358
	s_andn2_b64 vcc, exec, s[0:1]
	s_cbranch_vccz .LBB0_367

.LBB0_307:
	s_lshl_b32 s27, s20, 8
	s_add_i32 s0, s27, s77
	v_and_or_b32 v192, v2, 15, s0
	s_lshl_b32 s0, s56, 8
	s_ashr_i32 s1, s0, 31
	v_ashrrev_i32_e32 v0, 4, v2
	s_lshl_b64 s[0:1], s[0:1], 2
	v_lshlrev_b32_e32 v194, 3, v0
	s_add_u32 s0, s66, s0
	s_addc_u32 s1, s67, s1
	v_ashrrev_i32_e32 v195, 31, v194
	v_ashrrev_i32_e32 v193, 31, v192
	v_or_b32_e32 v206, 16, v192
	v_or_b32_e32 v208, 32, v192
	v_or_b32_e32 v210, 48, v192
	v_lshl_add_u64 v[6:7], v[194:195], 2, s[0:1]
	v_lshl_add_u64 v[146:147], v[192:193], 2, s[86:87]
	v_ashrrev_i32_e32 v207, 31, v206
	v_ashrrev_i32_e32 v209, 31, v208
	v_ashrrev_i32_e32 v211, 31, v210
	v_mov_b64_e32 v[10:11], v[220:221]
	v_mov_b64_e32 v[12:13], v[222:223]
	v_mov_b64_e32 v[14:15], v[224:225]
	v_mov_b64_e32 v[16:17], v[226:227]
	v_mov_b64_e32 v[2:3], v[228:229]
	v_mov_b64_e32 v[4:5], v[230:231]
	s_nop 0
	v_mov_b64_e32 v[6:7], v[232:233]
	v_mov_b64_e32 v[8:9], v[234:235]
	v_lshl_add_u64 v[148:149], v[206:207], 2, s[86:87]
	v_lshl_add_u64 v[150:151], v[208:209], 2, s[86:87]
	v_lshl_add_u64 v[152:153], v[210:211], 2, s[86:87]
	v_mov_b32_e32 v190, v236
	v_mov_b32_e32 v188, v237
	v_mov_b32_e32 v186, v238
	v_mov_b32_e32 v182, v239
	v_mov_b32_e32 v180, v240
	v_mov_b32_e32 v178, v241
	v_mov_b32_e32 v176, v242
	v_mov_b32_e32 v174, v243
	s_lshl_b32 s0, s18, 8
	s_ashr_i32 s31, s30, 31
	s_and_b32 s19, s0, 0x700
	s_lshl_b64 s[0:1], s[30:31], 25
	v_readlane_b32 s28, v251, 30
	s_add_u32 s0, s28, s0
	v_readlane_b32 s28, v251, 31
	v_add_u32_e32 v184, 0x80, v192
	v_add_u32_e32 v212, 0x90, v192
	v_add_u32_e32 v204, 0xa0, v192
	v_add_u32_e32 v202, 0xb0, v192
	s_addc_u32 s1, s28, s1
	s_or_b32 s19, s19, s14
	v_ashrrev_i32_e32 v185, 31, v184
	v_ashrrev_i32_e32 v213, 31, v212
	v_ashrrev_i32_e32 v205, 31, v204
	v_ashrrev_i32_e32 v203, 31, v202
	v_add_u32_e32 v200, s19, v194
	s_mov_b64 s[34:35], -1
	s_mov_b64 s[28:29], 0
	s_bitcmp1_b32 s60, 8
	s_cbranch_scc1 .Lebar_skip_300
	s_barrier
.Lebar_skip_300:
	s_cmp_lt_i32 s49, 3
	s_mov_b64 s[42:43], 0
	s_cbranch_scc1 .LBB0_347
	s_cmp_gt_i32 s49, 3
	s_cbranch_scc0 .LBB0_344
	s_cmp_eq_u32 s49, 4
	s_mov_b64 s[42:43], -1
	s_cbranch_scc0 .LBB0_343
	v_cvt_f32_i32_e32 v147, v127
	v_cvt_f32_i32_e32 v146, v126
	v_cvt_f32_i32_e32 v151, v129
	v_cvt_f32_i32_e32 v150, v128
	v_readlane_b32 s34, v255, 14
	v_pk_mul_f32 v[148:149], v[190:191], v[6:7] op_sel_hi:[0,1]
	v_readlane_b32 s35, v255, 15
	v_pk_mul_f32 v[146:147], v[148:149], v[146:147]
	v_pk_mul_f32 v[148:149], v[190:191], v[8:9] op_sel_hi:[0,1]
	v_cndmask_b32_e64 v152, 0, 1, s[34:35]
	v_cmp_ne_u32_e64 s[42:43], 1, v152
	s_andn2_b64 vcc, exec, s[34:35]
	v_pk_mul_f32 v[148:149], v[148:149], v[150:151]
	s_cbranch_vccnz .LBB0_312
	v_mul_f32_e32 v150, 0xbfb8aa3b, v146
	v_mul_f32_e32 v151, 0xbfb8aa3b, v147
	v_mul_f32_e32 v152, 0xbfb8aa3b, v148
	v_mul_f32_e32 v153, 0xbfb8aa3b, v149
	v_exp_f32_e32 v150, v150
	v_exp_f32_e32 v151, v151
	v_exp_f32_e32 v152, v152
	v_exp_f32_e32 v153, v153
	v_add_f32_e32 v150, 1.0, v150
	v_add_f32_e32 v151, 1.0, v151
	v_add_f32_e32 v152, 1.0, v152
	v_add_f32_e32 v153, 1.0, v153
	v_rcp_f32_e32 v150, v150
	v_rcp_f32_e32 v151, v151
	v_rcp_f32_e32 v152, v152
	v_rcp_f32_e32 v153, v153
	v_pk_mul_f32 v[146:147], v[146:147], v[150:151]
	v_pk_mul_f32 v[148:149], v[148:149], v[152:153]
